# t26 + phi-copy v_mov pairs merged into v_pk_mov_b32, masked/skip path of the neighbourhood-attention step loops back without the O round-trip copies, 24 dead pad bytes keep downstream loop alignment
# speedup vs baseline: 1.0058x; 1.0000x over previous
; #define LAS __attribute__((address_space(3)))
; #define MFMA32(a, b, c) __builtin_amdgcn_mfma_f32_32x32x16_bf16((a), (b), (c), 0, 0, 0)
; #define WG_BAR() do { asm volatile("s_waitcnt lgkmcnt(0)" ::: "memory"); __builtin_amdgcn_s_barrier(); asm volatile("" ::: "memory"); } while (0)
; #define ATT_DMA(t) do { const int t_ = (t) < NS ? (t) : NS - 1; const size_t ro_ = (size_t)TILE_ROW(t_) * ZC; LAS unsigned char* d_ = dk0 + ((t) % ATT_NB) * KV_BUF; \
;         __builtin_amdgcn_global_load_lds((const unsigned*)(gk + ro_), (LAS unsigned*)d_, 16, 0, 0); __builtin_amdgcn_global_load_lds((const unsigned*)(gv + ro_), (LAS unsigned*)(d_ + KV_TILE), 16, 0, 0); } while (0)
; template <class ScoreFn>
; __device__ __forceinline__ void attn_step(AttnState& st, const bf16x8 (&qf)[4], LAS unsigned char* kb, LAS unsigned char* vb, int lane, const ScoreFn& sf) {
;     ...
;     LAS unsigned char* kp = kb + r * KVP; const int kx = (h ^ (r & 7)) << 4;
; #pragma unroll
;     for (int ds = 0; ds < 4; ++ds) {
;         const bf16x8 k0 = *(const LAS bf16x8*)(kp + (kx ^ (ds << 5))), k1 = *(const LAS bf16x8*)(kp + 32 * KVP + (kx ^ (ds << 5)));
;         s0 = MFMA32(k0, qf[ds], s0); s1 = MFMA32(k1, qf[ds], s1);
;     }
;     float mt = NEG_BIG;
;     __builtin_amdgcn_sched_barrier(0);
; #pragma unroll
;     for (int i = 0; i < 16; ++i) { s0[i] = sf(s0[i], (i & 3) + 8 * (i >> 2), h, r); mt = fmaxf(mt, s0[i]); if ((i & 7) == 7) __builtin_amdgcn_sched_barrier(0); }
; #pragma unroll
;     for (int i = 0; i < 16; ++i) { s1[i] = sf(s1[i], 32 + (i & 3) + 8 * (i >> 2), h, r); mt = fmaxf(mt, s1[i]); if ((i & 7) == 7) __builtin_amdgcn_sched_barrier(0); }
;     mt = fmaxf(mt, __shfl_xor(mt, 32));
; template <bool ISB>
; __device__ __forceinline__ void attn_wg_item(Frame& F, int l, int idx) {
;     ...
;     AttnState st;
; #pragma unroll
;     for (int i = 0; i < 16; ++i) { st.o0[i] = 0.f; st.o1[i] = 0.f; }
;     st.m = NEG_BIG; st.l = 0.f;
; #pragma unroll
;     for (int t = 0; t < ATT_D; ++t) ATT_DMA(t);
;     if (ISB && lat) {
;         const float* bsrc = KIN(I_NBBIAS) + (size_t)(l * 8 + (ix & 7)) * 465;
;         if (tid < 465) tab[64 + tid] = bsrc[tid] * LOG2E; }
;     for (int s = 0; s < NS; ++s) {
;         ATT_DMA(s + ATT_D);
;         asm volatile("s_waitcnt vmcnt(8)" ::: "memory");
;         WG_BAR();
;         LAS unsigned char* cur = ring + (s % ATT_NB) * KV_BUF;
.LBB0_581:
	s_mul_hi_u32 s1, s16, 0xaaaaaaab
	s_mul_hi_u32 s2, s13, 0xaaaaaaab
	s_lshr_b32 s1, s1, 2
	s_lshr_b32 s2, s2, 2
	s_mul_i32 s1, s1, 0x18000
	s_mul_i32 s2, s2, 0x18000
	v_readlane_b32 s3, v253, 15
	s_sub_i32 s1, s15, s1
	v_add3_u32 v126, s1, v104, v89
	v_add3_u32 v125, s1, v96, v89
	v_add3_u32 v127, s1, v103, v89
	v_add3_u32 v124, s1, v95, v89
	v_add3_u32 v122, s1, v102, v89
	v_add3_u32 v123, s1, v101, v89
	v_add3_u32 v119, s1, v94, v89
	v_add3_u32 v120, s1, v93, v89
	v_add3_u32 v117, s1, v100, v89
	v_add3_u32 v118, s1, v99, v89
	v_add3_u32 v115, s1, v92, v89
	v_add3_u32 v116, s1, v91, v89
	v_add3_u32 v113, s1, v98, v89
	v_add3_u32 v114, s1, v97, v89
	v_add3_u32 v111, s1, v90, v89
	v_add3_u32 v112, s1, v88, v89
	v_add_u32_e32 v128, s1, v105
	s_sub_i32 s8, s3, s2
	v_add_u32_e32 v130, s1, v106
	v_add_u32_e32 v131, s1, v107
	v_add_u32_e32 v132, s1, v108
	s_add_i32 s1, s16, 4
	s_cmp_lt_i32 s16, s11
	s_cselect_b64 s[2:3], -1, 0
	s_and_b64 vcc, s[2:3], exec
	s_cselect_b32 s1, s1, s12
	s_cmp_lt_i32 s1, s11
	s_cselect_b32 s2, 0, s11
	s_cselect_b32 s3, s10, 0x2000
	s_sub_i32 s1, s1, s2
	s_lshl_b32 s1, s1, 6
	s_add_i32 s1, s1, s3
	s_add_i32 s2, s15, s8
	v_pk_mov_b32 v[84:85], v[2:3], v[2:3] op_sel:[0,1]
	s_add_i32 s8, s2, 0
	v_mad_i64_i32 v[2:3], s[2:3], s1, v249, v[50:51]
	s_add_i32 m0, s8, 0x10000
	v_lshl_add_u64 v[4:5], v[2:3], 0, s[18:19]
	global_load_lds_dwordx4 v[4:5], off
	v_lshl_add_u64 v[2:3], v[2:3], 0, s[20:21]
	s_add_i32 m0, s8, 0x12000
	v_pk_mov_b32 v[82:83], v[18:19], v[18:19] op_sel:[0,1]
	global_load_lds_dwordx4 v[2:3], off
	s_waitcnt vmcnt(8)
	s_waitcnt lgkmcnt(0)
	s_barrier
	s_mov_b64 s[8:9], -1
	s_cbranch_vccnz .LBB0_583
	s_mov_b32 s1, 0
	v_add_u32_e32 v6, s1, v132
	ds_read_b128 v[2:5], v6
	ds_read_b128 v[18:21], v6 offset:4096
	v_add_u32_e32 v26, s1, v131
	ds_read_b128 v[22:25], v26
	ds_read_b128 v[134:137], v26 offset:4096
	v_add_u32_e32 v27, s1, v130
	v_add_u32_e32 v26, s1, v128
	s_waitcnt lgkmcnt(0)
	v_mfma_f32_32x32x16_bf16 v[2:17], v[2:5], v[34:37], 0
	ds_read_b128 v[138:141], v27 offset:4096
	v_mfma_f32_32x32x16_bf16 v[2:17], v[22:25], v[38:41], v[2:17]
	ds_read_b128 v[22:25], v27
	s_waitcnt lgkmcnt(0)
	v_mfma_f32_32x32x16_bf16 v[2:17], v[22:25], v[42:45], v[2:17]
	ds_read_b128 v[22:25], v26
	ds_read_b128 v[142:145], v26 offset:4096
	s_waitcnt lgkmcnt(0)
	v_mfma_f32_32x32x16_bf16 v[2:17], v[22:25], v[46:49], v[2:17]
	v_mfma_f32_32x32x16_bf16 v[18:33], v[18:21], v[34:37], 0
	v_mfma_f32_32x32x16_bf16 v[18:33], v[134:137], v[38:41], v[18:33]
	v_mfma_f32_32x32x16_bf16 v[18:33], v[138:141], v[42:45], v[18:33]
	v_mfma_f32_32x32x16_bf16 v[18:33], v[142:145], v[46:49], v[18:33]
	s_nop 7
	s_mov_b32 s1, 0xf149f2ca
	v_max3_f32 v66, v2, v3, v4
	v_max3_f32 v66, v66, v5, v6
	v_max3_f32 v66, v66, v7, v8
	v_max3_f32 v66, v66, v9, v10
	v_max3_f32 v66, v66, v11, v12
	v_max3_f32 v66, v66, v13, v14
	v_max3_f32 v66, v66, v15, v16
	v_max3_f32 v66, v66, v17, v18
	v_max3_f32 v66, v66, v19, v20
	v_max3_f32 v66, v66, v21, v22
	v_max3_f32 v66, v66, v23, v24
	v_max3_f32 v66, v66, v25, v26
	v_max3_f32 v66, v66, v27, v28
	v_max3_f32 v66, v66, v29, v30
	v_max3_f32 v66, v66, v31, v32
	v_max_f32_e32 v66, v66, v33
	v_cmp_lt_i32_e32 vcc, v242, v241
	v_mul_f32_e32 v66, 0x3e38aa3b, v66
	v_max_f32_e32 v66, s1, v66
	v_cndmask_b32_e32 v121, v240, v242, vcc
	v_lshlrev_b32_e32 v121, 2, v121
	ds_bpermute_b32 v121, v121, v66
	s_waitcnt lgkmcnt(0)
; #define LAS __attribute__((address_space(3)))
; #define MFMA32(a, b, c) __builtin_amdgcn_mfma_f32_32x32x16_bf16((a), (b), (c), 0, 0, 0)
; __device__ __forceinline__ unsigned cvtpk(float lo, float hi) { return pg8::cvt_pk_bf16(lo, hi); }
; template <class ScoreFn>
; __device__ __forceinline__ void attn_step(AttnState& st, const bf16x8 (&qf)[4], LAS unsigned char* kb, LAS unsigned char* vb, int lane, const ScoreFn& sf) {
;     ...
;     mt = fmaxf(mt, __shfl_xor(mt, 32));
;     const float mn = fmaxf(st.m, mt), alpha = __builtin_amdgcn_exp2f(st.m - mn);
;     float ps = 0.f;
; #pragma unroll
;     for (int i = 0; i < 16; ++i) { s0[i] = __builtin_amdgcn_exp2f(s0[i] - mn); s1[i] = __builtin_amdgcn_exp2f(s1[i] - mn); ps += s0[i] + s1[i]; }
;     st.l = st.l * alpha + ps; st.m = mn;
; #pragma unroll
;     for (int i = 0; i < 16; ++i) { st.o0[i] *= alpha; st.o1[i] *= alpha; }
;     __builtin_amdgcn_sched_barrier(0);
;     v4u pw[4];
;     pw[0].x = cvtpk(s0[0], s0[1]); pw[0].y = cvtpk(s0[2], s0[3]); pw[0].z = cvtpk(s0[4], s0[5]); pw[0].w = cvtpk(s0[6], s0[7]);
;     pw[1].x = cvtpk(s0[8], s0[9]); pw[1].y = cvtpk(s0[10], s0[11]); pw[1].z = cvtpk(s0[12], s0[13]); pw[1].w = cvtpk(s0[14], s0[15]);
;     pw[2].x = cvtpk(s1[0], s1[1]); pw[2].y = cvtpk(s1[2], s1[3]); pw[2].z = cvtpk(s1[4], s1[5]); pw[2].w = cvtpk(s1[6], s1[7]);
;     pw[3].x = cvtpk(s1[8], s1[9]); pw[3].y = cvtpk(s1[10], s1[11]); pw[3].z = cvtpk(s1[12], s1[13]); pw[3].w = cvtpk(s1[14], s1[15]);
;     const int i16 = lane & 15, q = i16 >> 2, p = i16 & 3, dhalf = (lane >> 4) & 1;
;     LAS unsigned char* vrow = vb + (4 * h + q) * KVP + (p & 1) * 8;
;     LAS unsigned char* vp0 = vrow + (((2 * dhalf + (p >> 1)) ^ (4 * h + q)) << 4); LAS unsigned char* vp1 = vrow + (((4 + 2 * dhalf + (p >> 1)) ^ (4 * h + q)) << 4);
; #pragma unroll
;     for (int ks = 0; ks < 4; ++ks) {
;         const s16x4 l0 = tr_read(vp0 + (16 * ks) * KVP), h0 = tr_read(vp0 + (16 * ks + 8) * KVP);
;         const s16x4 l1 = tr_read(vp1 + (16 * ks) * KVP), h1 = tr_read(vp1 + (16 * ks + 8) * KVP);
;         const bf16x8 v0 = (bf16x8){l0[0], l0[1], l0[2], l0[3], h0[0], h0[1], h0[2], h0[3]};
;         const bf16x8 v1 = (bf16x8){l1[0], l1[1], l1[2], l1[3], h1[0], h1[1], h1[2], h1[3]};
;         const bf16x8 pf = __builtin_bit_cast(bf16x8, pw[ks]);
;         st.o0 = MFMA32(v0, pf, st.o0); st.o1 = MFMA32(v1, pf, st.o1);
;     }
	v_max3_f32 v121, v110, v66, v121
	v_pk_fma_f32 v[2:3], v[2:3], s[0:1], v[120:121] op_sel:[0,0,1] op_sel_hi:[1,0,1] neg_lo:[0,0,1] neg_hi:[0,0,1]
	v_pk_fma_f32 v[18:19], v[18:19], s[0:1], v[120:121] op_sel:[0,0,1] op_sel_hi:[1,0,1] neg_lo:[0,0,1] neg_hi:[0,0,1]
	v_exp_f32_e32 v133, v2
	v_exp_f32_e32 v165, v18
	v_exp_f32_e32 v66, v3
	v_exp_f32_e32 v142, v19
	v_add_f32_e32 v143, v165, v133
	v_pk_add_f32 v[2:3], v[142:143], v[66:67]
	s_nop 0
	v_pk_add_f32 v[136:137], v[2:3], v[2:3] op_sel_hi:[0,1]
	v_pk_fma_f32 v[4:5], v[4:5], s[0:1], v[120:121] op_sel:[0,0,1] op_sel_hi:[1,0,1] neg_lo:[0,0,1] neg_hi:[0,0,1]
	v_pk_fma_f32 v[20:21], v[20:21], s[0:1], v[120:121] op_sel:[0,0,1] op_sel_hi:[1,0,1] neg_lo:[0,0,1] neg_hi:[0,0,1]
	v_exp_f32_e32 v135, v4
	v_exp_f32_e32 v143, v20
	v_exp_f32_e32 v136, v5
	v_exp_f32_e32 v144, v21
	v_add_f32_e32 v145, v143, v135
	v_pk_add_f32 v[2:3], v[144:145], v[136:137]
	s_nop 0
	v_pk_add_f32 v[138:139], v[2:3], v[2:3] op_sel_hi:[0,1]
	v_pk_fma_f32 v[6:7], v[6:7], s[0:1], v[120:121] op_sel:[0,0,1] op_sel_hi:[1,0,1] neg_lo:[0,0,1] neg_hi:[0,0,1]
	v_pk_fma_f32 v[22:23], v[22:23], s[0:1], v[120:121] op_sel:[0,0,1] op_sel_hi:[1,0,1] neg_lo:[0,0,1] neg_hi:[0,0,1]
	v_exp_f32_e32 v137, v6
	v_exp_f32_e32 v145, v22
	v_exp_f32_e32 v138, v7
	v_exp_f32_e32 v146, v23
	v_add_f32_e32 v147, v145, v137
	v_pk_add_f32 v[2:3], v[146:147], v[138:139]
	s_nop 0
	v_pk_add_f32 v[140:141], v[2:3], v[2:3] op_sel_hi:[0,1]
	v_pk_fma_f32 v[8:9], v[8:9], s[0:1], v[120:121] op_sel:[0,0,1] op_sel_hi:[1,0,1] neg_lo:[0,0,1] neg_hi:[0,0,1]
	v_pk_fma_f32 v[24:25], v[24:25], s[0:1], v[120:121] op_sel:[0,0,1] op_sel_hi:[1,0,1] neg_lo:[0,0,1] neg_hi:[0,0,1]
	v_exp_f32_e32 v139, v8
	v_exp_f32_e32 v147, v24
	v_exp_f32_e32 v140, v9
	v_exp_f32_e32 v148, v25
	v_add_f32_e32 v149, v147, v139
	v_pk_add_f32 v[2:3], v[148:149], v[140:141]
	s_nop 0
	v_pk_add_f32 v[150:151], v[2:3], v[2:3] op_sel_hi:[0,1]
	v_pk_fma_f32 v[10:11], v[10:11], s[0:1], v[120:121] op_sel:[0,0,1] op_sel_hi:[1,0,1] neg_lo:[0,0,1] neg_hi:[0,0,1]
	v_pk_fma_f32 v[26:27], v[26:27], s[0:1], v[120:121] op_sel:[0,0,1] op_sel_hi:[1,0,1] neg_lo:[0,0,1] neg_hi:[0,0,1]
	v_exp_f32_e32 v141, v10
	v_exp_f32_e32 v149, v26
	v_exp_f32_e32 v150, v11
	v_exp_f32_e32 v152, v27
	v_add_f32_e32 v153, v149, v141
	v_pk_add_f32 v[2:3], v[152:153], v[150:151]
	s_nop 0
	v_pk_add_f32 v[154:155], v[2:3], v[2:3] op_sel_hi:[0,1]
	v_pk_fma_f32 v[12:13], v[12:13], s[0:1], v[120:121] op_sel:[0,0,1] op_sel_hi:[1,0,1] neg_lo:[0,0,1] neg_hi:[0,0,1]
	v_pk_fma_f32 v[28:29], v[28:29], s[0:1], v[120:121] op_sel:[0,0,1] op_sel_hi:[1,0,1] neg_lo:[0,0,1] neg_hi:[0,0,1]
	v_exp_f32_e32 v151, v12
	v_exp_f32_e32 v153, v28
	v_exp_f32_e32 v154, v13
	v_exp_f32_e32 v156, v29
	v_add_f32_e32 v157, v153, v151
	v_pk_add_f32 v[2:3], v[156:157], v[154:155]
	s_nop 0
	v_pk_add_f32 v[158:159], v[2:3], v[2:3] op_sel_hi:[0,1]
	v_pk_fma_f32 v[14:15], v[14:15], s[0:1], v[120:121] op_sel:[0,0,1] op_sel_hi:[1,0,1] neg_lo:[0,0,1] neg_hi:[0,0,1]
	v_pk_fma_f32 v[30:31], v[30:31], s[0:1], v[120:121] op_sel:[0,0,1] op_sel_hi:[1,0,1] neg_lo:[0,0,1] neg_hi:[0,0,1]
	v_exp_f32_e32 v155, v14
	v_exp_f32_e32 v157, v30
	v_exp_f32_e32 v158, v15
	v_exp_f32_e32 v160, v31
	v_add_f32_e32 v161, v157, v155
	v_pk_add_f32 v[2:3], v[160:161], v[158:159]
	s_nop 0
	v_pk_add_f32 v[162:163], v[2:3], v[2:3] op_sel_hi:[0,1]
	v_pk_fma_f32 v[16:17], v[16:17], s[0:1], v[120:121] op_sel:[0,0,1] op_sel_hi:[1,0,1] neg_lo:[0,0,1] neg_hi:[0,0,1]
	v_pk_fma_f32 v[32:33], v[32:33], s[0:1], v[120:121] op_sel:[0,0,1] op_sel_hi:[1,0,1] neg_lo:[0,0,1] neg_hi:[0,0,1]
	v_exp_f32_e32 v159, v16
	v_exp_f32_e32 v161, v32
	v_exp_f32_e32 v162, v17
	v_exp_f32_e32 v166, v33
	v_sub_f32_e32 v2, v110, v121
	v_exp_f32_e32 v18, v2
	v_add_f32_e32 v167, v161, v159
	v_pk_add_f32 v[2:3], v[166:167], v[162:163]
	v_pk_mul_f32 v[16:17], v[80:81], v[18:19] op_sel_hi:[1,0]
	v_add_f32_e32 v129, v2, v3
	v_fmac_f32_e32 v129, v109, v18
	v_pk_mul_f32 v[14:15], v[76:77], v[18:19] op_sel_hi:[1,0]
	v_pk_mul_f32 v[12:13], v[72:73], v[18:19] op_sel_hi:[1,0]
	v_pk_mul_f32 v[10:11], v[68:69], v[18:19] op_sel_hi:[1,0]
	v_pk_mul_f32 v[8:9], v[62:63], v[18:19] op_sel_hi:[1,0]
	v_pk_mul_f32 v[6:7], v[58:59], v[18:19] op_sel_hi:[1,0]
	v_pk_mul_f32 v[4:5], v[54:55], v[18:19] op_sel_hi:[1,0]
	v_pk_mul_f32 v[2:3], v[84:85], v[18:19] op_sel_hi:[1,0]
	v_pk_mul_f32 v[32:33], v[78:79], v[18:19] op_sel_hi:[1,0]
	v_pk_mul_f32 v[30:31], v[74:75], v[18:19] op_sel_hi:[1,0]
	v_pk_mul_f32 v[28:29], v[70:71], v[18:19] op_sel_hi:[1,0]
	v_pk_mul_f32 v[26:27], v[64:65], v[18:19] op_sel_hi:[1,0]
	v_pk_mul_f32 v[24:25], v[60:61], v[18:19] op_sel_hi:[1,0]
	v_pk_mul_f32 v[22:23], v[56:57], v[18:19] op_sel_hi:[1,0]
	v_pk_mul_f32 v[20:21], v[52:53], v[18:19] op_sel_hi:[1,0]
	v_pk_mul_f32 v[18:19], v[82:83], v[18:19] op_sel_hi:[1,0]
	v_cvt_pk_bf16_f32 v135, v135, v136
	v_cvt_pk_bf16_f32 v136, v137, v138
	v_cvt_pk_bf16_f32 v137, v139, v140
	v_cvt_pk_bf16_f32 v138, v141, v150
	v_cvt_pk_bf16_f32 v139, v151, v154
	v_cvt_pk_bf16_f32 v140, v155, v158
	v_cvt_pk_bf16_f32 v143, v143, v144
	v_cvt_pk_bf16_f32 v144, v145, v146
	v_cvt_pk_bf16_f32 v145, v147, v148
	v_cvt_pk_bf16_f32 v146, v149, v152
	v_cvt_pk_bf16_f32 v147, v153, v156
	v_cvt_pk_bf16_f32 v148, v157, v160
	ds_read_b64_tr_b16 v[150:151], v126
	ds_read_b64_tr_b16 v[152:153], v127
	ds_read_b64_tr_b16 v[154:155], v125
	ds_read_b64_tr_b16 v[156:157], v124
	v_cvt_pk_bf16_f32 v134, v133, v66
	v_cvt_pk_bf16_f32 v141, v159, v162
	v_cvt_pk_bf16_f32 v142, v165, v142
	s_waitcnt lgkmcnt(2)
	v_mfma_f32_32x32x16_bf16 v[2:17], v[150:153], v[134:137], v[2:17]
	v_cvt_pk_bf16_f32 v149, v161, v166
	s_mov_b64 s[8:9], 0
	s_waitcnt lgkmcnt(0)
	v_mfma_f32_32x32x16_bf16 v[18:33], v[154:157], v[134:137], v[18:33]
	ds_read_b64_tr_b16 v[134:135], v122
	ds_read_b64_tr_b16 v[136:137], v123
	ds_read_b64_tr_b16 v[150:151], v119
	ds_read_b64_tr_b16 v[152:153], v120
	s_waitcnt lgkmcnt(2)
	v_mfma_f32_32x32x16_bf16 v[2:17], v[134:137], v[138:141], v[2:17]
	s_waitcnt lgkmcnt(0)
	v_mfma_f32_32x32x16_bf16 v[18:33], v[150:153], v[138:141], v[18:33]
	ds_read_b64_tr_b16 v[134:135], v117
	ds_read_b64_tr_b16 v[136:137], v118
	ds_read_b64_tr_b16 v[138:139], v115
	ds_read_b64_tr_b16 v[140:141], v116
	s_waitcnt lgkmcnt(2)
	v_mfma_f32_32x32x16_bf16 v[2:17], v[134:137], v[142:145], v[2:17]
	s_waitcnt lgkmcnt(0)
	v_mfma_f32_32x32x16_bf16 v[18:33], v[138:141], v[142:145], v[18:33]
	ds_read_b64_tr_b16 v[134:135], v113
	ds_read_b64_tr_b16 v[136:137], v114
	ds_read_b64_tr_b16 v[138:139], v111
	ds_read_b64_tr_b16 v[140:141], v112
	s_waitcnt lgkmcnt(2)
	v_mfma_f32_32x32x16_bf16 v[2:17], v[134:137], v[146:149], v[2:17]
	s_waitcnt lgkmcnt(0)
	v_mfma_f32_32x32x16_bf16 v[18:33], v[138:141], v[146:149], v[18:33]

; #define LAS __attribute__((address_space(3)))
; #define WG_BAR() do { asm volatile("s_waitcnt lgkmcnt(0)" ::: "memory"); __builtin_amdgcn_s_barrier(); asm volatile("" ::: "memory"); } while (0)
; #define ATT_DMA(t) do { const int t_ = (t) < NS ? (t) : NS - 1; const size_t ro_ = (size_t)TILE_ROW(t_) * ZC; LAS unsigned char* d_ = dk0 + ((t) % ATT_NB) * KV_BUF; \
;         __builtin_amdgcn_global_load_lds((const unsigned*)(gk + ro_), (LAS unsigned*)d_, 16, 0, 0); __builtin_amdgcn_global_load_lds((const unsigned*)(gv + ro_), (LAS unsigned*)(d_ + KV_TILE), 16, 0, 0); } while (0)
; template <bool ISB>
; __device__ __forceinline__ void attn_wg_item(Frame& F, int l, int idx) {
;     ...
;     for (int s = 0; s < NS; ++s) {
;         ATT_DMA(s + ATT_D);
;         asm volatile("s_waitcnt vmcnt(8)" ::: "memory");
;         WG_BAR();
;         LAS unsigned char* cur = ring + (s % ATT_NB) * KV_BUF;
;         if (s >= nloc) { ScorePlain sf; attn_step(st, qf, cur, cur + KV_TILE, lane, sf); }
;         else if (!ISB) { int dkv = krow_base + 64 * s - qrow0; asm volatile("" : "+v"(dkv)); ScoreWin sf{dkv}; attn_step(st, qf, cur, cur + KV_TILE, lane, sf); }
.LBB0_585:
	s_add_i32 s14, s14, 64
	s_addk_i32 s15, 0x4000
	s_add_i32 s13, s13, 1
	s_add_i32 s1, s16, 1
	s_cmp_lg_u32 s16, s12
	s_cbranch_scc0 .LBB0_588
	v_mov_b32_e32 v109, v129
	s_mov_b32 s16, s1
	v_mov_b32_e32 v110, v121
	s_nop 0
	v_pk_mov_b32 v[54:55], v[4:5], v[4:5] op_sel:[0,1]
	v_pk_mov_b32 v[58:59], v[6:7], v[6:7] op_sel:[0,1]
	v_pk_mov_b32 v[62:63], v[8:9], v[8:9] op_sel:[0,1]
	v_pk_mov_b32 v[68:69], v[10:11], v[10:11] op_sel:[0,1]
	v_pk_mov_b32 v[72:73], v[12:13], v[12:13] op_sel:[0,1]
	v_pk_mov_b32 v[76:77], v[14:15], v[14:15] op_sel:[0,1]
	v_pk_mov_b32 v[80:81], v[16:17], v[16:17] op_sel:[0,1]
	v_pk_mov_b32 v[52:53], v[20:21], v[20:21] op_sel:[0,1]
	v_pk_mov_b32 v[56:57], v[22:23], v[22:23] op_sel:[0,1]
	v_pk_mov_b32 v[60:61], v[24:25], v[24:25] op_sel:[0,1]
	v_pk_mov_b32 v[64:65], v[26:27], v[26:27] op_sel:[0,1]
	v_pk_mov_b32 v[70:71], v[28:29], v[28:29] op_sel:[0,1]
	v_pk_mov_b32 v[74:75], v[30:31], v[30:31] op_sel:[0,1]
	v_pk_mov_b32 v[78:79], v[32:33], v[32:33] op_sel:[0,1]
	s_branch .LBB0_581

; #define LAS __attribute__((address_space(3)))
; #define WG_BAR() do { asm volatile("s_waitcnt lgkmcnt(0)" ::: "memory"); __builtin_amdgcn_s_barrier(); asm volatile("" ::: "memory"); } while (0)
; #define ATT_DMA(t) do { const int t_ = (t) < NS ? (t) : NS - 1; const size_t ro_ = (size_t)TILE_ROW(t_) * ZC; LAS unsigned char* d_ = dk0 + ((t) % ATT_NB) * KV_BUF; \
;         __builtin_amdgcn_global_load_lds((const unsigned*)(gk + ro_), (LAS unsigned*)d_, 16, 0, 0); __builtin_amdgcn_global_load_lds((const unsigned*)(gv + ro_), (LAS unsigned*)(d_ + KV_TILE), 16, 0, 0); } while (0)
; template <bool ISB>
; __device__ __forceinline__ void attn_wg_item(Frame& F, int l, int idx) {
;     ...
;     for (int s = 0; s < NS; ++s) {
;         ATT_DMA(s + ATT_D);
;         asm volatile("s_waitcnt vmcnt(8)" ::: "memory");
;         WG_BAR();
;         LAS unsigned char* cur = ring + (s % ATT_NB) * KV_BUF;
;         if (s >= nloc) { ScorePlain sf; attn_step(st, qf, cur, cur + KV_TILE, lane, sf); }
;         else if (!ISB) { int dkv = krow_base + 64 * s - qrow0; asm volatile("" : "+v"(dkv)); ScoreWin sf{dkv}; attn_step(st, qf, cur, cur + KV_TILE, lane, sf); }
;         else { const int gr = r0 + (w >> 1); int kr0 = gr - 4; kr0 = kr0 < 0 ? 0 : (kr0 > 120 ? 120 : kr0); const int kr = kmin + s;
;             if (kr >= kr0 && kr < kr0 + 8) { const int cq = 32 * (w & 1) + (lane & 31), hh = lane >> 5; int cs = cq - 8; cs = cs < 0 ? 0 : (cs > 48 ? 48 : cs);
;                 ScoreNb sf{(LAS unsigned char*)(tab + 64) + ((kr - gr + 7) * 31 + 15 - cq + 4 * hh) * 4, cs - 4 * hh}; attn_step(st, qf, cur, cur + KV_TILE, lane, sf); } }
;     }
.LBB0_623:
	s_addk_i32 s81, 0x4000
	s_add_i32 s80, s80, 1
	s_add_i32 s1, s82, 1
	s_cmp_lg_u32 s82, s79
	v_add_u32_e32 v109, 0x7c, v109
	s_cbranch_scc0 .Lb623_exit
	s_mov_b32 s82, s1
	s_branch .LBB0_618
.Lb623_exit:
	v_mov_b32_e32 v140, v131
	v_mov_b32_e32 v141, v130
	s_nop 8
	v_mov_b32_e32 v34, v18
	v_mov_b32_e32 v35, v19
	v_mov_b32_e32 v36, v20
	v_mov_b32_e32 v37, v21
	v_mov_b32_e32 v38, v22
	v_mov_b32_e32 v39, v23
	v_mov_b32_e32 v40, v24
	v_mov_b32_e32 v41, v25
	v_mov_b32_e32 v42, v26
	v_mov_b32_e32 v43, v27
	v_mov_b32_e32 v44, v28
	v_mov_b32_e32 v45, v29
	v_mov_b32_e32 v46, v30
	v_mov_b32_e32 v47, v31
	v_mov_b32_e32 v48, v32
	v_mov_b32_e32 v49, v33
	v_mov_b32_e32 v50, v2
	v_mov_b32_e32 v51, v3
	v_mov_b32_e32 v52, v4
	v_mov_b32_e32 v53, v5
	v_mov_b32_e32 v54, v6
	v_mov_b32_e32 v55, v7
	v_mov_b32_e32 v56, v8
	v_mov_b32_e32 v57, v9
	v_mov_b32_e32 v58, v10
	v_mov_b32_e32 v59, v11
	v_mov_b32_e32 v60, v12
	v_mov_b32_e32 v61, v13
	v_mov_b32_e32 v62, v14
	v_mov_b32_e32 v63, v15
	v_mov_b32_e32 v64, v16
	v_mov_b32_e32 v65, v17
	s_branch .LBB0_626
	s_nop 0
	s_nop 0
	s_nop 0
	s_nop 0
	s_nop 0
	s_nop 0
.LBB0_624:
	s_addk_i32 s81, 0x4000
	s_add_i32 s80, s80, 1
	s_add_i32 s1, s82, 1
	s_cmp_lg_u32 s82, s79
	v_add_u32_e32 v109, 0x7c, v109
	s_cbranch_scc0 .LBB0_626
	v_mov_b32_e32 v130, v141
	s_mov_b32 s82, s1
	v_mov_b32_e32 v131, v140
	s_nop 0
	v_pk_mov_b32 v[2:3], v[50:51], v[50:51] op_sel:[0,1]
	v_pk_mov_b32 v[4:5], v[52:53], v[52:53] op_sel:[0,1]
	v_pk_mov_b32 v[6:7], v[54:55], v[54:55] op_sel:[0,1]
	v_pk_mov_b32 v[8:9], v[56:57], v[56:57] op_sel:[0,1]
	v_pk_mov_b32 v[10:11], v[58:59], v[58:59] op_sel:[0,1]
	v_pk_mov_b32 v[12:13], v[60:61], v[60:61] op_sel:[0,1]
	v_pk_mov_b32 v[14:15], v[62:63], v[62:63] op_sel:[0,1]
	v_pk_mov_b32 v[16:17], v[64:65], v[64:65] op_sel:[0,1]
	v_pk_mov_b32 v[18:19], v[34:35], v[34:35] op_sel:[0,1]
	v_pk_mov_b32 v[20:21], v[36:37], v[36:37] op_sel:[0,1]
	v_pk_mov_b32 v[22:23], v[38:39], v[38:39] op_sel:[0,1]
	v_pk_mov_b32 v[24:25], v[40:41], v[40:41] op_sel:[0,1]
	v_pk_mov_b32 v[26:27], v[42:43], v[42:43] op_sel:[0,1]
	v_pk_mov_b32 v[28:29], v[44:45], v[44:45] op_sel:[0,1]
	v_pk_mov_b32 v[30:31], v[46:47], v[46:47] op_sel:[0,1]
	v_pk_mov_b32 v[32:33], v[48:49], v[48:49] op_sel:[0,1]
	s_branch .LBB0_618
